# NA per-wave tickets claimed two per atomic (paired dequeue) on top of v34
# baseline (speedup 1.0000x reference)
; __device__ __forceinline__ void na_task(ParamsCP pp, int layer, int b, int h, int r, int g, int lane_in) {
;     int lane = lane_in; asm volatile("" : "+v"(lane));
;     const bf16_t* PROJ = (const bf16_t*)(pp->ws + WS_BIG + BIG_PROJ); const bf16_t* VT = (const bf16_t*)(pp->ws + WS_BIG + BIG_VT);
;     const float* misc = (const float*)(pp->ws + WS_MISC) + 16 * layer;
;     const float bound = misc[2];
;     const float* rpb = pp->in[13] + (size_t)layer * 7440 + (size_t)h * 465;
; __device__ __forceinline__ void mixer_phase(ParamsCP pp, int layer, LAS unsigned char* lds, int tid) {
;     ...
;     for (;;) {
;         unsigned t = 0;
;         if (lane == 0) t = atomicAdd(ctrn, 1u);
.LBB0_451:
	s_add_u32 s4, s78, s52
	s_addc_u32 s5, s79, s53
	s_add_u32 s86, s4, 0x8008
	s_addc_u32 s87, s5, 0
	v_readlane_b32 s4, v254, 49
	v_and_b32_e32 v110, 63, v206
	s_mul_i32 s30, s4, 0x1d10
	s_add_u32 s76, s78, 0x22780000
	v_cmp_eq_u32_e64 s[6:7], 0, v110
	s_addc_u32 s77, s79, 0
	s_lshl_b64 s[48:49], s[30:31], 2
	v_mov_b32_e32 v250, 1
	s_branch .LBB0_454

; __device__ __forceinline__ void mixer_phase(ParamsCP pp, int layer, LAS unsigned char* lds, int tid) {
;     ...
;     for (;;) {
;         unsigned t = 0;
;         if (lane == 0) t = atomicAdd(ctrn, 1u);
;         t = (unsigned)__builtin_amdgcn_readfirstlane((int)t);
;         if (t >= (unsigned)T_NATOTAL) break;
;         int q = (int)t;
.LBB0_454:
	v_readfirstlane_b32 s8, v250
	s_add_i32 s8, s8, 1
	s_and_b32 s4, s8, 1
	s_cmp_lg_u32 s4, 0
	s_cbranch_scc1 .Lna_have
	v_mov_b32_e32 v0, 0
	s_and_saveexec_b64 s[4:5], s[6:7]
	s_cbranch_execz .LBB0_458
	s_mov_b64 s[10:11], exec
	v_mbcnt_lo_u32_b32 v0, s10, 0
	v_mbcnt_hi_u32_b32 v0, s11, v0
	v_cmp_eq_u32_e32 vcc, 0, v0
	s_and_saveexec_b64 s[8:9], vcc
	s_cbranch_execz .LBB0_457
	s_bcnt1_i32_b64 s10, s[10:11]
	v_mov_b32_e32 v2, 2
	global_atomic_add v2, v1, v2, s[80:81] offset:512 sc0
